# finmerge: one poller per block at the first epilogue, plain row-sum reload for prompt panels
# speedup vs baseline: 1.0102x; 1.0102x over previous
.LBB0_153:
	s_lshl_b32 s6, s6, 8
	s_add_i32 s6, s6, s50
	v_or_b32_e32 v152, s6, v166
	v_readlane_b32 s7, v244, 2
	s_cmp_eq_u32 s7, 0
	s_cbranch_scc1 .Lfm1_done
	v_cmp_eq_u32_e32 vcc, 0, v147
	s_and_saveexec_b64 s[92:93], vcc
	s_cbranch_execz .Lfm1_join
	v_readlane_b32 s94, v244, 4
	v_readlane_b32 s95, v244, 5
	s_nop 4
.Lfm1_poll:
	global_load_dword v128, v137, s[94:95] sc1
	s_waitcnt vmcnt(0)
	v_readfirstlane_b32 s96, v128
	s_cmp_ge_u32 s96, s7
	s_cbranch_scc1 .Lfm1_join
	s_sleep 1
	s_branch .Lfm1_poll
.Lfm1_join:
	s_mov_b64 exec, s[92:93]
	s_barrier
	s_mov_b32 s7, 0
	v_writelane_b32 v244, s7, 2
	s_andn2_b64 vcc, exec, s[78:79]
	s_cbranch_vccnz .Lfm1_done
	v_mov_b32_e32 v128, v152
	v_ashrrev_i32_e32 v129, 31, v152
	v_lshl_add_u64 v[128:129], v[128:129], 2, s[16:17]
	s_cmp_lt_u32 s6, 0x4000
	s_cbranch_scc0 .Lfm1_sample
	global_load_dword v167, v[128:129], off
	global_load_dword v168, v[128:129], off offset:64
	global_load_dword v169, v[128:129], off offset:128
	global_load_dword v170, v[128:129], off offset:192
	global_load_dword v171, v[128:129], off offset:512
	global_load_dword v172, v[128:129], off offset:576
	global_load_dword v174, v[128:129], off offset:640
	global_load_dword v173, v[128:129], off offset:704
	s_branch .Lfm1_done
.Lfm1_sample:
	global_load_dword v167, v[128:129], off sc1
	global_load_dword v168, v[128:129], off offset:64 sc1
	global_load_dword v169, v[128:129], off offset:128 sc1
	global_load_dword v170, v[128:129], off offset:192 sc1
	global_load_dword v171, v[128:129], off offset:512 sc1
	global_load_dword v172, v[128:129], off offset:576 sc1
	global_load_dword v174, v[128:129], off offset:640 sc1
	global_load_dword v173, v[128:129], off offset:704 sc1
